# v018 + priority dropped to 0 right after the 4th QK MFMA (softmax tail and vote run at base priority)
# speedup vs baseline: 1.0343x; 1.0013x over previous
.LBB0_605:
	s_setprio 1
	s_mul_hi_u32 s0, s46, 0xaaaaaaab
	s_lshr_b32 s0, s0, 1
	s_mul_i32 s0, s0, 0xffff4000
	s_add_i32 s0, s0, s57
	s_add_i32 s0, s0, s69
	v_add3_u32 v96, v193, s0, v173
	v_add3_u32 v122, v191, s0, v173
	v_add3_u32 v248, v192, s0, v173
	v_add3_u32 v249, v190, s0, v173
	ds_read_b128 v[114:117], v96
	ds_read_b128 v[122:125], v122
	ds_read_b128 v[118:121], v248
	ds_read_b128 v[206:209], v249
	s_add_i32 s0, s69, 0xffffc000
	s_and_b32 s0, s0, 0x4000
	v_add_u32_e32 v244, s0, v176
	v_add_u32_e32 v245, s0, v177
	v_add_u32_e32 v246, s0, v178
	v_add_u32_e32 v247, s0, v179
	ds_read_b64_tr_b16 v[228:229], v244 offset:49152
	ds_read_b64_tr_b16 v[230:231], v244 offset:51200
	ds_read_b64_tr_b16 v[232:233], v245 offset:49152
	ds_read_b64_tr_b16 v[234:235], v245 offset:51200
	ds_read_b64_tr_b16 v[236:237], v246 offset:49152
	ds_read_b64_tr_b16 v[238:239], v246 offset:51200
	ds_read_b64_tr_b16 v[240:241], v247 offset:49152
	ds_read_b64_tr_b16 v[242:243], v247 offset:51200
	v_exp_f32_e32 v112, v80
	v_exp_f32_e32 v113, v81
	s_waitcnt lgkmcnt(11)
	v_mfma_f32_32x32x16_bf16 v[96:111], v[114:117], v[140:143], v[64:79]
	v_exp_f32_e32 v114, v82
	v_exp_f32_e32 v115, v83
	v_exp_f32_e32 v116, v84
	v_exp_f32_e32 v117, v85
	v_add_f32_e32 v252, v112, v113
	s_waitcnt lgkmcnt(9)
	v_mfma_f32_32x32x16_bf16 v[96:111], v[118:121], v[136:139], v[96:111]
	v_exp_f32_e32 v118, v86
	v_exp_f32_e32 v119, v87
	v_add_f32_e32 v253, v114, v115
	v_exp_f32_e32 v120, v88
	v_add_f32_e32 v252, v116, v252
	v_exp_f32_e32 v121, v89
	v_add_f32_e32 v253, v117, v253
	v_mfma_f32_32x32x16_bf16 v[96:111], v[122:125], v[132:135], v[96:111]
	v_exp_f32_e32 v122, v90
	v_add_f32_e32 v252, v118, v252
	v_exp_f32_e32 v123, v91
	v_add_f32_e32 v253, v119, v253
	v_exp_f32_e32 v124, v92
	v_add_f32_e32 v252, v120, v252
	v_exp_f32_e32 v125, v93
	v_add_f32_e32 v253, v121, v253
	s_waitcnt lgkmcnt(8)
	v_mfma_f32_32x32x16_bf16 v[96:111], v[206:209], v[128:131], v[96:111]
	s_setprio 0
	v_exp_f32_e32 v126, v94
	v_add_f32_e32 v252, v122, v252
	v_exp_f32_e32 v127, v95
	v_add_f32_e32 v253, v123, v253
	v_add_f32_e32 v252, v124, v252
	v_add_f32_e32 v253, v125, v253
	v_add_f32_e32 v252, v126, v252
	v_add_f32_e32 v253, v127, v253
	v_add_f32_e32 v209, v252, v253
	v_cmp_nge_f32_e32 vcc, s56, v209
	s_cbranch_vccz .LBB0_607
	v_max_f32_e32 v112, v81, v81
	v_max_f32_e32 v113, v80, v80
	v_max_f32_e32 v112, v113, v112
	v_max3_f32 v112, v112, v82, v83
	v_max3_f32 v112, v112, v84, v85
	v_max3_f32 v112, v112, v86, v87
	v_max3_f32 v112, v112, v88, v89
	v_max3_f32 v112, v112, v90, v91
	v_max3_f32 v112, v112, v92, v93
	v_max3_f32 v112, v112, v94, v95
	v_mov_b32_e32 v113, v112
	s_nop 1
	v_permlane32_swap_b32_e32 v112, v113
	v_max3_f32 v121, v112, v113, 0
	v_sub_f32_e32 v80, v80, v121
	v_exp_f32_e32 v112, v80
	v_sub_f32_e32 v81, v81, v121
	v_exp_f32_e32 v113, v81
	v_sub_f32_e32 v81, v82, v121
	v_exp_f32_e32 v114, v81
	v_sub_f32_e32 v81, v83, v121
	v_exp_f32_e32 v115, v81
	v_sub_f32_e32 v81, v84, v121
	v_add_f32_e32 v117, 0, v112
	v_exp_f32_e32 v116, v81
	v_sub_f32_e32 v82, v85, v121
	v_add_f32_e32 v81, v113, v117
	v_exp_f32_e32 v117, v82
	v_sub_f32_e32 v82, v86, v121
	v_add_f32_e32 v81, v114, v81
	v_exp_f32_e32 v118, v82
	v_sub_f32_e32 v82, v87, v121
	v_add_f32_e32 v81, v115, v81
	v_exp_f32_e32 v119, v82
	v_sub_f32_e32 v82, v88, v121
	v_add_f32_e32 v81, v116, v81
	v_sub_f32_e32 v83, v89, v121
	v_exp_f32_e32 v120, v82
	v_exp_f32_e64 v80, -v121
	v_sub_f32_e32 v84, v90, v121
	v_sub_f32_e32 v85, v91, v121
	v_sub_f32_e32 v86, v92, v121
	v_sub_f32_e32 v87, v93, v121
	v_sub_f32_e32 v88, v94, v121
	v_sub_f32_e32 v89, v95, v121
	v_add_f32_e32 v81, v117, v81
	v_sub_f32_e32 v111, v111, v121
	v_sub_f32_e32 v110, v110, v121
	v_sub_f32_e32 v109, v109, v121
	v_sub_f32_e32 v108, v108, v121
	v_sub_f32_e32 v107, v107, v121
	v_sub_f32_e32 v106, v106, v121
	v_sub_f32_e32 v105, v105, v121
	v_sub_f32_e32 v104, v104, v121
	v_sub_f32_e32 v103, v103, v121
	v_sub_f32_e32 v102, v102, v121
	v_sub_f32_e32 v101, v101, v121
	v_sub_f32_e32 v100, v100, v121
	v_sub_f32_e32 v99, v99, v121
	v_sub_f32_e32 v98, v98, v121
	v_sub_f32_e32 v97, v97, v121
	v_sub_f32_e32 v96, v96, v121
	v_sub_f32_e32 v79, v79, v121
	v_sub_f32_e32 v78, v78, v121
	v_sub_f32_e32 v77, v77, v121
	v_sub_f32_e32 v76, v76, v121
	v_sub_f32_e32 v75, v75, v121
	v_sub_f32_e32 v74, v74, v121
	v_sub_f32_e32 v73, v73, v121
	v_sub_f32_e32 v72, v72, v121
	v_sub_f32_e32 v71, v71, v121
	v_sub_f32_e32 v70, v70, v121
	v_sub_f32_e32 v69, v69, v121
	v_sub_f32_e32 v68, v68, v121
	v_sub_f32_e32 v67, v67, v121
	v_sub_f32_e32 v66, v66, v121
	v_sub_f32_e32 v65, v65, v121
	v_sub_f32_e32 v64, v64, v121
	v_exp_f32_e32 v121, v83
	v_add_f32_e32 v81, v118, v81
	v_exp_f32_e32 v122, v84
	v_add_f32_e32 v81, v119, v81
	v_exp_f32_e32 v123, v85
	v_add_f32_e32 v81, v120, v81
	v_exp_f32_e32 v124, v86
	v_pk_mul_f32 v[62:63], v[62:63], v[80:81] op_sel_hi:[1,0]
	v_pk_mul_f32 v[60:61], v[60:61], v[80:81] op_sel_hi:[1,0]
	v_pk_mul_f32 v[58:59], v[58:59], v[80:81] op_sel_hi:[1,0]
	v_pk_mul_f32 v[56:57], v[56:57], v[80:81] op_sel_hi:[1,0]
	v_pk_mul_f32 v[54:55], v[54:55], v[80:81] op_sel_hi:[1,0]
	v_pk_mul_f32 v[52:53], v[52:53], v[80:81] op_sel_hi:[1,0]
	v_pk_mul_f32 v[50:51], v[50:51], v[80:81] op_sel_hi:[1,0]
	v_pk_mul_f32 v[48:49], v[48:49], v[80:81] op_sel_hi:[1,0]
	v_pk_mul_f32 v[46:47], v[46:47], v[80:81] op_sel_hi:[1,0]
	v_pk_mul_f32 v[44:45], v[44:45], v[80:81] op_sel_hi:[1,0]
	v_pk_mul_f32 v[42:43], v[42:43], v[80:81] op_sel_hi:[1,0]
	v_pk_mul_f32 v[40:41], v[40:41], v[80:81] op_sel_hi:[1,0]
	v_pk_mul_f32 v[38:39], v[38:39], v[80:81] op_sel_hi:[1,0]
	v_pk_mul_f32 v[36:37], v[36:37], v[80:81] op_sel_hi:[1,0]
	v_pk_mul_f32 v[34:35], v[34:35], v[80:81] op_sel_hi:[1,0]
	v_pk_mul_f32 v[32:33], v[32:33], v[80:81] op_sel_hi:[1,0]
	v_pk_mul_f32 v[30:31], v[30:31], v[80:81] op_sel_hi:[1,0]
	v_pk_mul_f32 v[28:29], v[28:29], v[80:81] op_sel_hi:[1,0]
	v_pk_mul_f32 v[26:27], v[26:27], v[80:81] op_sel_hi:[1,0]
	v_pk_mul_f32 v[24:25], v[24:25], v[80:81] op_sel_hi:[1,0]
	v_pk_mul_f32 v[22:23], v[22:23], v[80:81] op_sel_hi:[1,0]
	v_pk_mul_f32 v[20:21], v[20:21], v[80:81] op_sel_hi:[1,0]
	v_pk_mul_f32 v[18:19], v[18:19], v[80:81] op_sel_hi:[1,0]
	v_pk_mul_f32 v[16:17], v[16:17], v[80:81] op_sel_hi:[1,0]
	v_pk_mul_f32 v[14:15], v[14:15], v[80:81] op_sel_hi:[1,0]
	v_pk_mul_f32 v[12:13], v[12:13], v[80:81] op_sel_hi:[1,0]
	v_pk_mul_f32 v[10:11], v[10:11], v[80:81] op_sel_hi:[1,0]
	v_pk_mul_f32 v[8:9], v[8:9], v[80:81] op_sel_hi:[1,0]
	v_pk_mul_f32 v[6:7], v[6:7], v[80:81] op_sel_hi:[1,0]
	v_pk_mul_f32 v[4:5], v[4:5], v[80:81] op_sel_hi:[1,0]
	v_pk_mul_f32 v[2:3], v[2:3], v[80:81] op_sel_hi:[1,0]
	v_pk_mul_f32 v[0:1], v[0:1], v[80:81] op_sel_hi:[1,0]
	v_mul_f32_e32 v162, v162, v80
	v_add_f32_e32 v80, v121, v81
	v_exp_f32_e32 v125, v87
	v_add_f32_e32 v80, v122, v80
	v_exp_f32_e32 v126, v88
	v_add_f32_e32 v80, v123, v80
	v_exp_f32_e32 v127, v89
	v_add_f32_e32 v80, v124, v80
	v_add_f32_e32 v80, v125, v80
	v_add_f32_e32 v80, v126, v80
	v_add_f32_e32 v209, v127, v80

.LBB0_612:
	s_setprio 1
	s_mul_hi_u32 s0, s71, 0xaaaaaaab
	s_lshr_b32 s0, s0, 1
	s_mul_i32 s0, s0, 0xffff4000
	s_add_i32 s0, s0, s69
	v_add3_u32 v80, v193, s0, v173
	v_add3_u32 v81, v192, s0, v173
	ds_read_b128 v[112:115], v80
	ds_read_b128 v[120:123], v81
	ds_read_b64_tr_b16 v[228:229], v244 offset:57344
	ds_read_b64_tr_b16 v[230:231], v244 offset:59392
	ds_read_b64_tr_b16 v[232:233], v245 offset:57344
	ds_read_b64_tr_b16 v[234:235], v245 offset:59392
	ds_read_b64_tr_b16 v[236:237], v246 offset:57344
	ds_read_b64_tr_b16 v[238:239], v246 offset:59392
	ds_read_b64_tr_b16 v[240:241], v247 offset:57344
	ds_read_b64_tr_b16 v[242:243], v247 offset:59392
	v_exp_f32_e32 v116, v98
	v_exp_f32_e32 v118, v100
	v_exp_f32_e32 v119, v101
	v_exp_f32_e32 v117, v103
	v_add_f32_e32 v162, v209, v162
	s_waitcnt lgkmcnt(9)
	v_mfma_f32_32x32x16_bf16 v[80:95], v[112:115], v[140:143], v[64:79]
	v_exp_f32_e32 v112, v96
	v_exp_f32_e32 v113, v97
	v_exp_f32_e32 v115, v99
	v_add3_u32 v114, v191, s0, v173
	ds_read_b128 v[124:127], v114
	s_waitcnt lgkmcnt(9)
	v_mfma_f32_32x32x16_bf16 v[80:95], v[120:123], v[136:139], v[80:95]
	v_add_f32_e32 v252, v112, v113
	v_add_f32_e32 v253, v116, v115
	v_exp_f32_e32 v120, v102
	v_add_f32_e32 v252, v118, v252
	v_add3_u32 v122, v190, s0, v173
	v_add_f32_e32 v253, v119, v253
	ds_read_b128 v[210:213], v122
	v_exp_f32_e32 v114, v104
	v_add_f32_e32 v252, v120, v252
	v_exp_f32_e32 v121, v105
	v_add_f32_e32 v253, v117, v253
	v_exp_f32_e32 v122, v106
	v_add_f32_e32 v252, v114, v252
	v_add_f32_e32 v253, v121, v253
	s_waitcnt lgkmcnt(1)
	v_mfma_f32_32x32x16_bf16 v[80:95], v[124:127], v[132:135], v[80:95]
	v_exp_f32_e32 v123, v107
	v_add_f32_e32 v252, v122, v252
	v_exp_f32_e32 v124, v108
	s_waitcnt lgkmcnt(0)
	v_mfma_f32_32x32x16_bf16 v[80:95], v[210:213], v[128:131], v[80:95]
	s_setprio 0
	v_exp_f32_e32 v125, v109
	v_add_f32_e32 v253, v123, v253
	v_exp_f32_e32 v126, v110
	v_add_f32_e32 v252, v124, v252
	v_exp_f32_e32 v127, v111
	v_add_f32_e32 v253, v125, v253
	v_add_f32_e32 v252, v126, v252
	v_add_f32_e32 v253, v127, v253
	v_add_f32_e32 v163, v252, v253
	v_cmp_nge_f32_e32 vcc, s56, v163
	s_cbranch_vccz .LBB0_597
	v_max_f32_e32 v112, v97, v97
	v_max_f32_e32 v113, v96, v96
	v_max_f32_e32 v112, v113, v112
	v_max3_f32 v112, v112, v98, v99
	v_max3_f32 v112, v112, v100, v101
	v_max3_f32 v112, v112, v102, v103
	v_max3_f32 v112, v112, v104, v105
	v_max3_f32 v112, v112, v106, v107
	v_max3_f32 v112, v112, v108, v109
	v_max3_f32 v112, v112, v110, v111
	v_mov_b32_e32 v113, v112
	s_nop 1
	v_permlane32_swap_b32_e32 v112, v113
	v_max3_f32 v121, v112, v113, 0
	v_sub_f32_e32 v96, v96, v121
	v_exp_f32_e32 v112, v96
	v_sub_f32_e32 v97, v97, v121
	v_exp_f32_e32 v113, v97
	v_sub_f32_e32 v97, v98, v121
	v_exp_f32_e32 v116, v97
	v_sub_f32_e32 v97, v99, v121
	v_exp_f32_e32 v115, v97
	v_sub_f32_e32 v97, v100, v121
	v_add_f32_e32 v114, 0, v112
	v_exp_f32_e32 v118, v97
	v_sub_f32_e32 v98, v101, v121
	v_add_f32_e32 v97, v113, v114
	v_exp_f32_e32 v119, v98
	v_sub_f32_e32 v98, v102, v121
	v_add_f32_e32 v97, v116, v97
	v_exp_f32_e32 v120, v98
	v_sub_f32_e32 v98, v103, v121
	v_add_f32_e32 v97, v115, v97
	v_exp_f32_e32 v117, v98
	v_sub_f32_e32 v98, v104, v121
	v_add_f32_e32 v97, v118, v97
	v_sub_f32_e32 v99, v105, v121
	v_exp_f32_e32 v114, v98
	v_exp_f32_e64 v96, -v121
	v_sub_f32_e32 v100, v106, v121
	v_sub_f32_e32 v101, v107, v121
	v_sub_f32_e32 v102, v108, v121
	v_sub_f32_e32 v103, v109, v121
	v_sub_f32_e32 v104, v110, v121
	v_sub_f32_e32 v105, v111, v121
	v_add_f32_e32 v97, v119, v97
	v_sub_f32_e32 v95, v95, v121
	v_sub_f32_e32 v94, v94, v121
	v_sub_f32_e32 v93, v93, v121
	v_sub_f32_e32 v92, v92, v121
	v_sub_f32_e32 v91, v91, v121
	v_sub_f32_e32 v90, v90, v121
	v_sub_f32_e32 v89, v89, v121
	v_sub_f32_e32 v88, v88, v121
	v_sub_f32_e32 v87, v87, v121
	v_sub_f32_e32 v86, v86, v121
	v_sub_f32_e32 v85, v85, v121
	v_sub_f32_e32 v84, v84, v121
	v_sub_f32_e32 v83, v83, v121
	v_sub_f32_e32 v82, v82, v121
	v_sub_f32_e32 v81, v81, v121
	v_sub_f32_e32 v80, v80, v121
	v_sub_f32_e32 v79, v79, v121
	v_sub_f32_e32 v78, v78, v121
	v_sub_f32_e32 v77, v77, v121
	v_sub_f32_e32 v76, v76, v121
	v_sub_f32_e32 v75, v75, v121
	v_sub_f32_e32 v74, v74, v121
	v_sub_f32_e32 v73, v73, v121
	v_sub_f32_e32 v72, v72, v121
	v_sub_f32_e32 v71, v71, v121
	v_sub_f32_e32 v70, v70, v121
	v_sub_f32_e32 v69, v69, v121
	v_sub_f32_e32 v68, v68, v121
	v_sub_f32_e32 v67, v67, v121
	v_sub_f32_e32 v66, v66, v121
	v_sub_f32_e32 v65, v65, v121
	v_sub_f32_e32 v64, v64, v121
	v_exp_f32_e32 v121, v99
	v_add_f32_e32 v97, v120, v97
	v_exp_f32_e32 v122, v100
	v_add_f32_e32 v97, v117, v97
	v_exp_f32_e32 v123, v101
	v_add_f32_e32 v97, v114, v97
	v_exp_f32_e32 v124, v102
	v_pk_mul_f32 v[62:63], v[62:63], v[96:97] op_sel_hi:[1,0]
	v_pk_mul_f32 v[60:61], v[60:61], v[96:97] op_sel_hi:[1,0]
	v_pk_mul_f32 v[58:59], v[58:59], v[96:97] op_sel_hi:[1,0]
	v_pk_mul_f32 v[56:57], v[56:57], v[96:97] op_sel_hi:[1,0]
	v_pk_mul_f32 v[54:55], v[54:55], v[96:97] op_sel_hi:[1,0]
	v_pk_mul_f32 v[52:53], v[52:53], v[96:97] op_sel_hi:[1,0]
	v_pk_mul_f32 v[50:51], v[50:51], v[96:97] op_sel_hi:[1,0]
	v_pk_mul_f32 v[48:49], v[48:49], v[96:97] op_sel_hi:[1,0]
	v_pk_mul_f32 v[46:47], v[46:47], v[96:97] op_sel_hi:[1,0]
	v_pk_mul_f32 v[44:45], v[44:45], v[96:97] op_sel_hi:[1,0]
	v_pk_mul_f32 v[42:43], v[42:43], v[96:97] op_sel_hi:[1,0]
	v_pk_mul_f32 v[40:41], v[40:41], v[96:97] op_sel_hi:[1,0]
	v_pk_mul_f32 v[38:39], v[38:39], v[96:97] op_sel_hi:[1,0]
	v_pk_mul_f32 v[36:37], v[36:37], v[96:97] op_sel_hi:[1,0]
	v_pk_mul_f32 v[34:35], v[34:35], v[96:97] op_sel_hi:[1,0]
	v_pk_mul_f32 v[32:33], v[32:33], v[96:97] op_sel_hi:[1,0]
	v_pk_mul_f32 v[30:31], v[30:31], v[96:97] op_sel_hi:[1,0]
	v_pk_mul_f32 v[28:29], v[28:29], v[96:97] op_sel_hi:[1,0]
	v_pk_mul_f32 v[26:27], v[26:27], v[96:97] op_sel_hi:[1,0]
	v_pk_mul_f32 v[24:25], v[24:25], v[96:97] op_sel_hi:[1,0]
	v_pk_mul_f32 v[22:23], v[22:23], v[96:97] op_sel_hi:[1,0]
	v_pk_mul_f32 v[20:21], v[20:21], v[96:97] op_sel_hi:[1,0]
	v_pk_mul_f32 v[18:19], v[18:19], v[96:97] op_sel_hi:[1,0]
	v_pk_mul_f32 v[16:17], v[16:17], v[96:97] op_sel_hi:[1,0]
	v_pk_mul_f32 v[14:15], v[14:15], v[96:97] op_sel_hi:[1,0]
	v_pk_mul_f32 v[12:13], v[12:13], v[96:97] op_sel_hi:[1,0]
	v_pk_mul_f32 v[10:11], v[10:11], v[96:97] op_sel_hi:[1,0]
	v_pk_mul_f32 v[8:9], v[8:9], v[96:97] op_sel_hi:[1,0]
	v_pk_mul_f32 v[6:7], v[6:7], v[96:97] op_sel_hi:[1,0]
	v_pk_mul_f32 v[4:5], v[4:5], v[96:97] op_sel_hi:[1,0]
	v_pk_mul_f32 v[2:3], v[2:3], v[96:97] op_sel_hi:[1,0]
	v_pk_mul_f32 v[0:1], v[0:1], v[96:97] op_sel_hi:[1,0]
	v_mul_f32_e32 v162, v162, v96
	v_add_f32_e32 v96, v121, v97
	v_exp_f32_e32 v125, v103
	v_add_f32_e32 v96, v122, v96
	v_exp_f32_e32 v126, v104
	v_add_f32_e32 v96, v123, v96
	v_exp_f32_e32 v127, v105
	v_add_f32_e32 v96, v124, v96
	v_add_f32_e32 v96, v125, v96
	v_add_f32_e32 v96, v126, v96
	v_add_f32_e32 v163, v127, v96
	s_branch .LBB0_597
